# phase-4 hid stores nontemporal
# baseline (speedup 1.0000x reference)
.LBB0_1095:
	v_lshl_or_b32 v122, s68, 8, v184
	v_ashrrev_i32_e32 v123, 31, v122
	v_lshl_add_u32 v201, s67, 8, v182
	v_lshlrev_b64 v[124:125], 2, v[122:123]
	v_lshlrev_b32_e32 v128, 1, v201
	v_or_b32_e32 v122, 16, v122
	v_ashrrev_i32_e32 v129, 31, v128
	v_ashrrev_i32_e32 v123, 31, v122
	v_lshl_add_u64 v[126:127], s[14:15], 0, v[124:125]
	v_lshl_add_u64 v[128:129], v[128:129], 2, s[82:83]
	v_lshlrev_b64 v[122:123], 2, v[122:123]
	global_load_dwordx2 v[202:203], v[128:129], off
	global_load_dwordx2 v[216:217], v[128:129], off offset:256
	global_load_dwordx2 v[218:219], v[128:129], off offset:384
	global_load_dwordx2 v[220:221], v[128:129], off offset:1024
	global_load_dwordx2 v[222:223], v[128:129], off offset:1152
	global_load_dwordx2 v[224:225], v[128:129], off offset:1280
	global_load_dwordx2 v[226:227], v[128:129], off offset:1408
	global_load_dwordx4 v[154:157], v[126:127], off
	global_load_dwordx4 v[146:149], v[126:127], off offset:512
	v_lshl_add_u64 v[126:127], s[14:15], 0, v[122:123]
	global_load_dwordx4 v[138:141], v[126:127], off
	s_nop 0
	global_load_dwordx4 v[126:129], v[126:127], off offset:512
	v_lshl_add_u64 v[124:125], s[18:19], 0, v[124:125]
	v_lshl_add_u64 v[122:123], s[18:19], 0, v[122:123]
	global_load_dwordx4 v[158:161], v[124:125], off
	global_load_dwordx4 v[150:153], v[124:125], off offset:512
	global_load_dwordx4 v[142:145], v[122:123], off
	s_nop 0
	global_load_dwordx4 v[122:125], v[122:123], off offset:512
	v_readlane_b32 s0, v251, 40
	v_lshl_or_b32 v178, s68, 7, v184
	v_readlane_b32 s1, v251, 41
	v_or_b32_e32 v210, 16, v201
	v_ashrrev_i32_e32 v179, 31, v178
	v_mov_b64_e32 v[176:177], s[0:1]
	v_lshlrev_b32_e32 v206, 1, v210
	v_mad_i64_i32 v[204:205], s[0:1], v201, s64, v[176:177]
	v_lshlrev_b64 v[178:179], 1, v[178:179]
	v_ashrrev_i32_e32 v207, 31, v206
	v_lshl_add_u64 v[204:205], v[204:205], 0, v[178:179]
	v_lshl_add_u64 v[206:207], v[206:207], 2, s[82:83]
	global_load_dwordx2 v[206:207], v[206:207], off
	s_mov_b32 s68, s65
	s_mov_b32 s67, s66
	s_mov_b64 s[26:27], s[54:55]
	s_mov_b64 s[28:29], s[8:9]
	s_waitcnt vmcnt(0)
	v_pk_mul_f32 v[202:203], v[202:203], s[46:47] op_sel_hi:[1,0]
	s_nop 0
	v_fma_f32 v211, -v202, v202, v203
	v_xor_b32_e32 v157, 0x80000000, v157
	v_pk_fma_f32 v[208:209], v[138:139], v[202:203], v[118:119] op_sel_hi:[1,0,1] neg_lo:[1,0,0] neg_hi:[1,0,0]
	v_xor_b32_e32 v119, 0x80000000, v141
	v_xor_b32_e32 v118, 0x80000000, v140
	v_pk_fma_f32 v[140:141], v[126:127], v[202:203], v[114:115] op_sel_hi:[1,0,1] neg_lo:[1,0,0] neg_hi:[1,0,0]
	v_add_f32_e32 v114, 0x3727c5ac, v211
	v_xor_b32_e32 v115, 0x80000000, v129
	v_mul_f32_e32 v129, 0x4b800000, v114
	v_cmp_gt_f32_e32 vcc, s63, v114
	v_xor_b32_e32 v156, 0x80000000, v156
	v_xor_b32_e32 v149, 0x80000000, v149
	v_cndmask_b32_e32 v114, v114, v129, vcc
	v_rsq_f32_e32 v129, v114
	v_xor_b32_e32 v114, 0x80000000, v128
	v_xor_b32_e32 v148, 0x80000000, v148
	v_pk_fma_f32 v[134:135], v[154:155], v[202:203], v[134:135] op_sel_hi:[1,0,1] neg_lo:[1,0,0] neg_hi:[1,0,0]
	v_mul_f32_e32 v128, 0x45800000, v129
	v_cndmask_b32_e32 v128, v129, v128, vcc
	v_pk_fma_f32 v[136:137], v[156:157], v[202:203], v[136:137] op_sel_hi:[1,0,1]
	v_pk_fma_f32 v[130:131], v[146:147], v[202:203], v[130:131] op_sel_hi:[1,0,1] neg_lo:[1,0,0] neg_hi:[1,0,0]
	v_pk_fma_f32 v[132:133], v[148:149], v[202:203], v[132:133] op_sel_hi:[1,0,1]
	v_pk_fma_f32 v[120:121], v[118:119], v[202:203], v[120:121] op_sel_hi:[1,0,1]
	v_pk_fma_f32 v[116:117], v[114:115], v[202:203], v[116:117] op_sel_hi:[1,0,1]
	v_pk_fma_f32 v[134:135], v[134:135], v[128:129], v[158:159] op_sel_hi:[1,0,1]
	v_pk_fma_f32 v[136:137], v[136:137], v[128:129], v[160:161] op_sel_hi:[1,0,1]
	v_pk_fma_f32 v[132:133], v[132:133], v[128:129], v[152:153] op_sel_hi:[1,0,1]
	v_pk_fma_f32 v[130:131], v[130:131], v[128:129], v[150:151] op_sel_hi:[1,0,1]
	v_pk_fma_f32 v[120:121], v[120:121], v[128:129], v[144:145] op_sel_hi:[1,0,1]
	v_pk_fma_f32 v[202:203], v[208:209], v[128:129], v[142:143] op_sel_hi:[1,0,1]
	v_pk_fma_f32 v[116:117], v[116:117], v[128:129], v[124:125] op_sel_hi:[1,0,1]
	v_pk_fma_f32 v[128:129], v[140:141], v[128:129], v[122:123] op_sel_hi:[1,0,1]
	v_mul_f32_e32 v140, 0xbfb8aa3b, v134
	v_mul_f32_e32 v141, 0xbfb8aa3b, v135
	v_exp_f32_e32 v140, v140
	v_mul_f32_e32 v208, 0xbfb8aa3b, v136
	v_mul_f32_e32 v209, 0xbfb8aa3b, v137
	v_exp_f32_e32 v141, v141
	v_exp_f32_e32 v208, v208
	v_exp_f32_e32 v209, v209
	v_add_f32_e32 v140, 1.0, v140
	v_add_f32_e32 v141, 1.0, v141
	v_rcp_f32_e32 v140, v140
	v_add_f32_e32 v208, 1.0, v208
	v_add_f32_e32 v209, 1.0, v209
	v_rcp_f32_e32 v141, v141
	v_mul_f32_e32 v213, 0xbfb8aa3b, v120
	v_rcp_f32_e32 v208, v208
	v_rcp_f32_e32 v209, v209
	v_mul_f32_e32 v211, 0xbfb8aa3b, v202
	v_mul_f32_e32 v212, 0xbfb8aa3b, v203
	v_mul_f32_e32 v214, 0xbfb8aa3b, v121
	v_exp_f32_e32 v213, v213
	v_exp_f32_e32 v211, v211
	v_exp_f32_e32 v212, v212
	v_exp_f32_e32 v214, v214
	v_mul_f32_e32 v134, v134, v140
	v_mul_f32_e32 v135, v135, v141
	v_mul_f32_e32 v130, v130, v134
	v_mul_f32_e32 v136, v136, v208
	v_mul_f32_e32 v137, v137, v209
	v_mul_f32_e32 v131, v131, v135
	v_cvt_pk_bf16_f32 v130, v130, v131
	v_mul_f32_e32 v132, v132, v136
	v_mul_f32_e32 v133, v133, v137
	v_cvt_pk_bf16_f32 v131, v132, v133
	global_store_dwordx2 v[204:205], v[130:131], off nt
	v_add_f32_e32 v130, 1.0, v213
	v_add_f32_e32 v211, 1.0, v211
	v_add_f32_e32 v212, 1.0, v212
	v_rcp_f32_e32 v130, v130
	v_add_f32_e32 v131, 1.0, v214
	v_rcp_f32_e32 v211, v211
	v_rcp_f32_e32 v212, v212
	v_rcp_f32_e32 v131, v131
	v_mul_f32_e32 v120, v120, v130
	v_mul_f32_e32 v140, v202, v211
	v_mul_f32_e32 v141, v203, v212
	v_mul_f32_e32 v120, v116, v120
	v_mul_f32_e32 v116, v121, v131
	v_mul_f32_e32 v128, v128, v140
	v_mul_f32_e32 v129, v129, v141
	v_mul_f32_e32 v117, v117, v116
	v_cvt_pk_bf16_f32 v116, v128, v129
	v_or_b32_e32 v134, 32, v201
	v_cvt_pk_bf16_f32 v117, v120, v117
	global_store_dwordx2 v[204:205], v[116:117], off offset:32 nt
	v_lshlrev_b32_e32 v116, 1, v134
	v_ashrrev_i32_e32 v117, 31, v116
	v_lshl_add_u64 v[116:117], v[116:117], 2, s[82:83]
	v_mov_b32_e32 v116, v216
	v_mov_b32_e32 v117, v217
	v_pk_mul_f32 v[128:129], v[206:207], s[46:47] op_sel_hi:[1,0]
	v_mad_i64_i32 v[120:121], s[0:1], v210, s64, v[176:177]
	v_mov_b32_e32 v131, v128
	v_mov_b32_e32 v133, v129
	v_pk_fma_f32 v[110:111], v[154:155], v[128:129], v[110:111] op_sel_hi:[1,0,1] neg_lo:[1,0,0] neg_hi:[1,0,0]
	v_pk_fma_f32 v[112:113], v[156:157], v[128:129], v[112:113] op_sel_hi:[1,0,1]
	v_pk_fma_f32 v[106:107], v[146:147], v[128:129], v[106:107] op_sel_hi:[1,0,1] neg_lo:[1,0,0] neg_hi:[1,0,0]
	v_pk_fma_f32 v[108:109], v[148:149], v[128:129], v[108:109] op_sel_hi:[1,0,1]
	v_pk_fma_f32 v[102:103], v[138:139], v[128:129], v[102:103] op_sel_hi:[1,0,1] neg_lo:[1,0,0] neg_hi:[1,0,0]
	v_pk_fma_f32 v[104:105], v[118:119], v[128:129], v[104:105] op_sel_hi:[1,0,1]
	v_pk_fma_f32 v[98:99], v[126:127], v[128:129], v[98:99] op_sel_hi:[1,0,1] neg_lo:[1,0,0] neg_hi:[1,0,0]
	v_pk_fma_f32 v[100:101], v[114:115], v[128:129], v[100:101] op_sel_hi:[1,0,1]
	v_lshl_add_u64 v[120:121], v[120:121], 0, v[178:179]
	v_pk_mul_f32 v[116:117], v[116:117], s[46:47] op_sel_hi:[1,0]
	s_nop 0
	v_mov_b32_e32 v130, v116
	v_mov_b32_e32 v132, v117
	v_pk_fma_f32 v[130:131], v[130:131], v[130:131], v[132:133] neg_lo:[1,0,0] neg_hi:[1,0,0]
	v_pk_fma_f32 v[94:95], v[154:155], v[116:117], v[94:95] op_sel_hi:[1,0,1] neg_lo:[1,0,0] neg_hi:[1,0,0]
	v_pk_add_f32 v[130:131], v[130:131], s[52:53] op_sel_hi:[1,0]
	v_pk_fma_f32 v[96:97], v[156:157], v[116:117], v[96:97] op_sel_hi:[1,0,1]
	v_mul_f32_e32 v132, 0x4b800000, v131
	v_cmp_gt_f32_e32 vcc, s63, v131
	v_mul_f32_e32 v133, 0x4b800000, v130
	v_cmp_gt_f32_e64 s[0:1], s63, v130
	v_cndmask_b32_e32 v131, v131, v132, vcc
	v_rsq_f32_e32 v131, v131
	v_cndmask_b32_e64 v130, v130, v133, s[0:1]
	v_rsq_f32_e32 v130, v130
	v_pk_fma_f32 v[90:91], v[146:147], v[116:117], v[90:91] op_sel_hi:[1,0,1] neg_lo:[1,0,0] neg_hi:[1,0,0]
	v_mul_f32_e32 v128, 0x45800000, v131
	v_cndmask_b32_e32 v128, v131, v128, vcc
	v_mul_f32_e32 v129, 0x45800000, v130
	v_pk_fma_f32 v[112:113], v[112:113], v[128:129], v[160:161] op_sel_hi:[1,0,1]
	v_pk_fma_f32 v[104:105], v[104:105], v[128:129], v[144:145] op_sel_hi:[1,0,1]
	v_pk_fma_f32 v[102:103], v[102:103], v[128:129], v[142:143] op_sel_hi:[1,0,1]
	v_pk_fma_f32 v[110:111], v[110:111], v[128:129], v[158:159] op_sel_hi:[1,0,1]
	v_mul_f32_e32 v131, 0xbfb8aa3b, v112
	v_mul_f32_e32 v132, 0xbfb8aa3b, v113
	v_mul_f32_e32 v135, 0xbfb8aa3b, v103
	v_mul_f32_e32 v137, 0xbfb8aa3b, v105
	v_cndmask_b32_e64 v130, v130, v129, s[0:1]
	v_pk_fma_f32 v[108:109], v[108:109], v[128:129], v[152:153] op_sel_hi:[1,0,1]
	v_pk_fma_f32 v[106:107], v[106:107], v[128:129], v[150:151] op_sel_hi:[1,0,1]
	v_pk_fma_f32 v[100:101], v[100:101], v[128:129], v[124:125] op_sel_hi:[1,0,1]
	v_pk_fma_f32 v[98:99], v[98:99], v[128:129], v[122:123] op_sel_hi:[1,0,1]
	v_mul_f32_e32 v128, 0xbfb8aa3b, v110
	v_mul_f32_e32 v129, 0xbfb8aa3b, v111
	v_mul_f32_e32 v133, 0xbfb8aa3b, v102
	v_mul_f32_e32 v136, 0xbfb8aa3b, v104
	v_exp_f32_e32 v131, v131
	v_exp_f32_e32 v132, v132
	v_exp_f32_e32 v135, v135
	v_exp_f32_e32 v137, v137
	v_exp_f32_e32 v128, v128
	v_exp_f32_e32 v129, v129
	v_exp_f32_e32 v133, v133
	v_exp_f32_e32 v136, v136
	v_add_f32_e32 v131, 1.0, v131
	v_add_f32_e32 v132, 1.0, v132
	v_add_f32_e32 v135, 1.0, v135
	v_add_f32_e32 v137, 1.0, v137
	v_add_f32_e32 v128, 1.0, v128
	v_add_f32_e32 v129, 1.0, v129
	v_add_f32_e32 v133, 1.0, v133
	v_add_f32_e32 v136, 1.0, v136
	v_rcp_f32_e32 v131, v131
	v_rcp_f32_e32 v132, v132
	v_rcp_f32_e32 v135, v135
	v_rcp_f32_e32 v137, v137
	v_rcp_f32_e32 v128, v128
	v_rcp_f32_e32 v129, v129
	v_rcp_f32_e32 v133, v133
	v_rcp_f32_e32 v136, v136
	v_mul_f32_e32 v112, v112, v131
	v_mul_f32_e32 v113, v113, v132
	v_mul_f32_e32 v103, v103, v135
	v_mul_f32_e32 v105, v105, v137
	v_mul_f32_e32 v110, v110, v128
	v_mul_f32_e32 v111, v111, v129
	v_mul_f32_e32 v102, v102, v133
	v_mul_f32_e32 v104, v104, v136
	v_mul_f32_e32 v108, v108, v112
	v_mul_f32_e32 v109, v109, v113
	v_mul_f32_e32 v103, v99, v103
	v_mul_f32_e32 v101, v101, v105
	v_cvt_pk_bf16_f32 v99, v108, v109
	v_pk_fma_f32 v[94:95], v[94:95], v[130:131], v[158:159] op_sel_hi:[1,0,1]
	v_mul_f32_e32 v106, v106, v110
	v_mul_f32_e32 v107, v107, v111
	v_mul_f32_e32 v102, v98, v102
	v_mul_f32_e32 v100, v100, v104
	v_cvt_pk_bf16_f32 v98, v106, v107
	global_store_dwordx2 v[120:121], v[98:99], off nt
	v_cvt_pk_bf16_f32 v99, v100, v101
	v_mul_f32_e32 v101, 0xbfb8aa3b, v94
	v_exp_f32_e32 v101, v101
	v_cvt_pk_bf16_f32 v98, v102, v103
	v_mul_f32_e32 v102, 0xbfb8aa3b, v95
	v_exp_f32_e32 v102, v102
	v_add_f32_e32 v101, 1.0, v101
	v_rcp_f32_e32 v101, v101
	v_pk_fma_f32 v[96:97], v[96:97], v[130:131], v[160:161] op_sel_hi:[1,0,1]
	v_pk_fma_f32 v[90:91], v[90:91], v[130:131], v[150:151] op_sel_hi:[1,0,1]
	v_pk_fma_f32 v[92:93], v[148:149], v[116:117], v[92:93] op_sel_hi:[1,0,1]
	v_mul_f32_e32 v94, v94, v101
	v_mul_f32_e32 v90, v90, v94
	v_add_f32_e32 v94, 1.0, v102
	v_mul_f32_e32 v101, 0xbfb8aa3b, v96
	v_rcp_f32_e32 v94, v94
	v_exp_f32_e32 v101, v101
	v_mul_f32_e32 v102, 0xbfb8aa3b, v97
	v_exp_f32_e32 v102, v102
	v_mul_f32_e32 v94, v95, v94
	v_add_f32_e32 v95, 1.0, v101
	v_rcp_f32_e32 v95, v95
	v_add_f32_e32 v101, 1.0, v102
	v_rcp_f32_e32 v101, v101
	v_pk_fma_f32 v[92:93], v[92:93], v[130:131], v[152:153] op_sel_hi:[1,0,1]
	v_mul_f32_e32 v91, v91, v94
	v_mul_f32_e32 v94, v96, v95
	v_or_b32_e32 v100, 48, v201
	v_mul_f32_e32 v92, v92, v94
	v_mul_f32_e32 v94, v97, v101
	global_store_dwordx2 v[120:121], v[98:99], off offset:32 nt
	v_lshlrev_b32_e32 v98, 1, v100
	v_mul_f32_e32 v93, v93, v94
	v_ashrrev_i32_e32 v99, 31, v98
	v_cvt_pk_bf16_f32 v90, v90, v91
	v_cvt_pk_bf16_f32 v91, v92, v93
	v_mad_i64_i32 v[92:93], s[0:1], v134, s64, v[176:177]
	v_pk_fma_f32 v[86:87], v[138:139], v[116:117], v[86:87] op_sel_hi:[1,0,1] neg_lo:[1,0,0] neg_hi:[1,0,0]
	v_lshl_add_u64 v[98:99], v[98:99], 2, s[82:83]
	v_lshl_add_u64 v[92:93], v[92:93], 0, v[178:179]
	v_pk_fma_f32 v[86:87], v[86:87], v[130:131], v[142:143] op_sel_hi:[1,0,1]
	v_mov_b32_e32 v98, v218
	v_mov_b32_e32 v99, v219
	v_pk_fma_f32 v[88:89], v[118:119], v[116:117], v[88:89] op_sel_hi:[1,0,1]
	global_store_dwordx2 v[92:93], v[90:91], off nt
	v_mul_f32_e32 v90, 0xbfb8aa3b, v86
	v_exp_f32_e32 v90, v90
	v_mul_f32_e32 v91, 0xbfb8aa3b, v87
	v_exp_f32_e32 v91, v91
	v_pk_fma_f32 v[82:83], v[126:127], v[116:117], v[82:83] op_sel_hi:[1,0,1] neg_lo:[1,0,0] neg_hi:[1,0,0]
	v_add_f32_e32 v90, 1.0, v90
	v_rcp_f32_e32 v90, v90
	v_pk_fma_f32 v[88:89], v[88:89], v[130:131], v[144:145] op_sel_hi:[1,0,1]
	v_pk_fma_f32 v[82:83], v[82:83], v[130:131], v[122:123] op_sel_hi:[1,0,1]
	v_pk_fma_f32 v[84:85], v[114:115], v[116:117], v[84:85] op_sel_hi:[1,0,1]
	v_mul_f32_e32 v86, v86, v90
	v_mul_f32_e32 v82, v82, v86
	v_add_f32_e32 v86, 1.0, v91
	v_mul_f32_e32 v90, 0xbfb8aa3b, v88
	v_rcp_f32_e32 v86, v86
	v_exp_f32_e32 v90, v90
	v_mul_f32_e32 v91, 0xbfb8aa3b, v89
	v_exp_f32_e32 v91, v91
	v_mul_f32_e32 v86, v87, v86
	v_add_f32_e32 v87, 1.0, v90
	v_rcp_f32_e32 v87, v87
	v_add_f32_e32 v90, 1.0, v91
	v_rcp_f32_e32 v90, v90
	v_pk_fma_f32 v[84:85], v[84:85], v[130:131], v[124:125] op_sel_hi:[1,0,1]
	v_mul_f32_e32 v83, v83, v86
	v_mul_f32_e32 v86, v88, v87
	v_mul_f32_e32 v84, v84, v86
	v_mul_f32_e32 v86, v89, v90
	v_cvt_pk_bf16_f32 v82, v82, v83
	v_add_u32_e32 v90, 0x80, v201
	v_mul_f32_e32 v85, v85, v86
	v_cvt_pk_bf16_f32 v83, v84, v85
	global_store_dwordx2 v[92:93], v[82:83], off offset:32 nt
	v_lshlrev_b32_e32 v82, 1, v90
	v_ashrrev_i32_e32 v83, 31, v82
	v_lshl_add_u64 v[82:83], v[82:83], 2, s[82:83]
	v_mov_b32_e32 v82, v220
	v_mov_b32_e32 v83, v221
	v_pk_mul_f32 v[84:85], v[98:99], s[46:47] op_sel_hi:[1,0]
	s_nop 0
	v_mov_b32_e32 v87, v84
	v_mov_b32_e32 v89, v85
	v_pk_fma_f32 v[78:79], v[154:155], v[84:85], v[78:79] op_sel_hi:[1,0,1] neg_lo:[1,0,0] neg_hi:[1,0,0]
	v_pk_fma_f32 v[80:81], v[156:157], v[84:85], v[80:81] op_sel_hi:[1,0,1]
	v_pk_fma_f32 v[76:77], v[148:149], v[84:85], v[76:77] op_sel_hi:[1,0,1]
	v_pk_fma_f32 v[74:75], v[146:147], v[84:85], v[74:75] op_sel_hi:[1,0,1] neg_lo:[1,0,0] neg_hi:[1,0,0]
	v_pk_fma_f32 v[70:71], v[138:139], v[84:85], v[70:71] op_sel_hi:[1,0,1] neg_lo:[1,0,0] neg_hi:[1,0,0]
	v_pk_fma_f32 v[72:73], v[118:119], v[84:85], v[72:73] op_sel_hi:[1,0,1]
	v_pk_fma_f32 v[66:67], v[126:127], v[84:85], v[66:67] op_sel_hi:[1,0,1] neg_lo:[1,0,0] neg_hi:[1,0,0]
	v_pk_fma_f32 v[68:69], v[114:115], v[84:85], v[68:69] op_sel_hi:[1,0,1]
	v_pk_mul_f32 v[82:83], v[82:83], s[46:47] op_sel_hi:[1,0]
	s_nop 0
	v_mov_b32_e32 v86, v82
	v_mov_b32_e32 v88, v83
	v_pk_fma_f32 v[86:87], v[86:87], v[86:87], v[88:89] neg_lo:[1,0,0] neg_hi:[1,0,0]
	v_pk_fma_f32 v[62:63], v[154:155], v[82:83], v[62:63] op_sel_hi:[1,0,1] neg_lo:[1,0,0] neg_hi:[1,0,0]
	v_pk_add_f32 v[86:87], v[86:87], s[52:53] op_sel_hi:[1,0]
	v_pk_fma_f32 v[64:65], v[156:157], v[82:83], v[64:65] op_sel_hi:[1,0,1]
	v_mul_f32_e32 v88, 0x4b800000, v87
	v_cmp_gt_f32_e32 vcc, s63, v87
	v_cmp_gt_f32_e64 s[0:1], s63, v86
	v_pk_fma_f32 v[58:59], v[146:147], v[82:83], v[58:59] op_sel_hi:[1,0,1] neg_lo:[1,0,0] neg_hi:[1,0,0]
	v_cndmask_b32_e32 v87, v87, v88, vcc
	v_mul_f32_e32 v88, 0x4b800000, v86
	v_rsq_f32_e32 v87, v87
	v_cndmask_b32_e64 v86, v86, v88, s[0:1]
	v_rsq_f32_e32 v88, v86
	v_pk_fma_f32 v[60:61], v[148:149], v[82:83], v[60:61] op_sel_hi:[1,0,1]
	v_mul_f32_e32 v86, 0x45800000, v87
	v_cndmask_b32_e32 v86, v87, v86, vcc
	v_mul_f32_e32 v87, 0x45800000, v88
	v_pk_fma_f32 v[78:79], v[78:79], v[86:87], v[158:159] op_sel_hi:[1,0,1]
	v_cndmask_b32_e64 v88, v88, v87, s[0:1]
	v_pk_fma_f32 v[80:81], v[80:81], v[86:87], v[160:161] op_sel_hi:[1,0,1]
	v_mul_f32_e32 v87, 0xbfb8aa3b, v78
	v_exp_f32_e32 v87, v87
	v_mul_f32_e32 v89, 0xbfb8aa3b, v79
	v_exp_f32_e32 v89, v89
	v_pk_fma_f32 v[54:55], v[138:139], v[82:83], v[54:55] op_sel_hi:[1,0,1] neg_lo:[1,0,0] neg_hi:[1,0,0]
	v_pk_fma_f32 v[76:77], v[76:77], v[86:87], v[152:153] op_sel_hi:[1,0,1]
	v_add_f32_e32 v87, 1.0, v87
	v_rcp_f32_e32 v87, v87
	v_pk_fma_f32 v[56:57], v[118:119], v[82:83], v[56:57] op_sel_hi:[1,0,1]
	v_pk_fma_f32 v[50:51], v[126:127], v[82:83], v[50:51] op_sel_hi:[1,0,1] neg_lo:[1,0,0] neg_hi:[1,0,0]
	v_pk_fma_f32 v[52:53], v[114:115], v[82:83], v[52:53] op_sel_hi:[1,0,1]
	v_pk_fma_f32 v[74:75], v[74:75], v[86:87], v[150:151] op_sel_hi:[1,0,1]
	v_mul_f32_e32 v78, v78, v87
	v_mul_f32_e32 v74, v74, v78
	v_add_f32_e32 v78, 1.0, v89
	v_mul_f32_e32 v87, 0xbfb8aa3b, v80
	v_rcp_f32_e32 v78, v78
	v_exp_f32_e32 v87, v87
	v_mul_f32_e32 v89, 0xbfb8aa3b, v81
	v_exp_f32_e32 v89, v89
	v_mul_f32_e32 v78, v79, v78
	v_add_f32_e32 v79, 1.0, v87
	v_rcp_f32_e32 v79, v79
	v_add_f32_e32 v87, 1.0, v89
	v_rcp_f32_e32 v87, v87
	v_mul_f32_e32 v75, v75, v78
	v_mul_f32_e32 v78, v80, v79
	v_mul_f32_e32 v76, v76, v78
	v_mul_f32_e32 v78, v81, v87
	v_mul_f32_e32 v77, v77, v78
	v_cvt_pk_bf16_f32 v74, v74, v75
	v_cvt_pk_bf16_f32 v75, v76, v77
	v_mad_i64_i32 v[76:77], s[0:1], v100, s64, v[176:177]
	v_lshl_add_u64 v[76:77], v[76:77], 0, v[178:179]
	v_pk_fma_f32 v[70:71], v[70:71], v[86:87], v[142:143] op_sel_hi:[1,0,1]
	global_store_dwordx2 v[76:77], v[74:75], off nt
	v_mul_f32_e32 v74, 0xbfb8aa3b, v70
	v_exp_f32_e32 v74, v74
	v_mul_f32_e32 v75, 0xbfb8aa3b, v71
	v_exp_f32_e32 v75, v75
	v_pk_fma_f32 v[72:73], v[72:73], v[86:87], v[144:145] op_sel_hi:[1,0,1]
	v_add_f32_e32 v74, 1.0, v74
	v_rcp_f32_e32 v74, v74
	v_pk_fma_f32 v[66:67], v[66:67], v[86:87], v[122:123] op_sel_hi:[1,0,1]
	v_pk_fma_f32 v[68:69], v[68:69], v[86:87], v[124:125] op_sel_hi:[1,0,1]
	v_pk_fma_f32 v[62:63], v[62:63], v[88:89], v[158:159] op_sel_hi:[1,0,1]
	v_mul_f32_e32 v70, v70, v74
	v_mul_f32_e32 v66, v66, v70
	v_add_f32_e32 v70, 1.0, v75
	v_mul_f32_e32 v74, 0xbfb8aa3b, v72
	v_rcp_f32_e32 v70, v70
	v_exp_f32_e32 v74, v74
	v_mul_f32_e32 v75, 0xbfb8aa3b, v73
	v_exp_f32_e32 v75, v75
	v_mul_f32_e32 v70, v71, v70
	v_add_f32_e32 v71, 1.0, v74
	v_rcp_f32_e32 v71, v71
	v_add_f32_e32 v74, 1.0, v75
	v_rcp_f32_e32 v74, v74
	v_mul_f32_e32 v67, v67, v70
	v_mul_f32_e32 v70, v72, v71
	v_mul_f32_e32 v68, v68, v70
	v_mul_f32_e32 v70, v73, v74
	v_mul_f32_e32 v69, v69, v70
	v_cvt_pk_bf16_f32 v66, v66, v67
	v_cvt_pk_bf16_f32 v67, v68, v69
	v_mul_f32_e32 v69, 0xbfb8aa3b, v62
	v_exp_f32_e32 v69, v69
	v_mul_f32_e32 v70, 0xbfb8aa3b, v63
	v_exp_f32_e32 v70, v70
	v_pk_fma_f32 v[64:65], v[64:65], v[88:89], v[160:161] op_sel_hi:[1,0,1]
	v_add_f32_e32 v69, 1.0, v69
	v_rcp_f32_e32 v69, v69
	v_pk_fma_f32 v[58:59], v[58:59], v[88:89], v[150:151] op_sel_hi:[1,0,1]
	v_pk_fma_f32 v[60:61], v[60:61], v[88:89], v[152:153] op_sel_hi:[1,0,1]
	v_add_u32_e32 v68, 0x90, v201
	v_mul_f32_e32 v62, v62, v69
	v_mul_f32_e32 v58, v58, v62
	v_add_f32_e32 v62, 1.0, v70
	v_mul_f32_e32 v69, 0xbfb8aa3b, v64
	v_rcp_f32_e32 v62, v62
	v_exp_f32_e32 v69, v69
	v_mul_f32_e32 v70, 0xbfb8aa3b, v65
	v_exp_f32_e32 v70, v70
	v_mul_f32_e32 v62, v63, v62
	v_add_f32_e32 v63, 1.0, v69
	v_rcp_f32_e32 v63, v63
	v_add_f32_e32 v69, 1.0, v70
	v_rcp_f32_e32 v69, v69
	v_mul_f32_e32 v59, v59, v62
	v_mul_f32_e32 v62, v64, v63
	v_mul_f32_e32 v60, v60, v62
	v_mul_f32_e32 v62, v65, v69
	global_store_dwordx2 v[76:77], v[66:67], off offset:32 nt
	v_lshlrev_b32_e32 v66, 1, v68
	v_mul_f32_e32 v61, v61, v62
	v_ashrrev_i32_e32 v67, 31, v66
	v_cvt_pk_bf16_f32 v58, v58, v59
	v_cvt_pk_bf16_f32 v59, v60, v61
	v_mad_i64_i32 v[60:61], s[0:1], v90, s64, v[176:177]
	v_lshl_add_u64 v[66:67], v[66:67], 2, s[82:83]
	v_lshl_add_u64 v[60:61], v[60:61], 0, v[178:179]
	v_pk_fma_f32 v[54:55], v[54:55], v[88:89], v[142:143] op_sel_hi:[1,0,1]
	v_mov_b32_e32 v66, v222
	v_mov_b32_e32 v67, v223
	v_pk_fma_f32 v[56:57], v[56:57], v[88:89], v[144:145] op_sel_hi:[1,0,1]
	global_store_dwordx2 v[60:61], v[58:59], off nt
	v_mul_f32_e32 v58, 0xbfb8aa3b, v54
	v_exp_f32_e32 v58, v58
	v_mul_f32_e32 v59, 0xbfb8aa3b, v55
	v_exp_f32_e32 v59, v59
	v_pk_fma_f32 v[50:51], v[50:51], v[88:89], v[122:123] op_sel_hi:[1,0,1]
	v_add_f32_e32 v58, 1.0, v58
	v_rcp_f32_e32 v58, v58
	v_pk_fma_f32 v[52:53], v[52:53], v[88:89], v[124:125] op_sel_hi:[1,0,1]
	v_mul_f32_e32 v54, v54, v58
	v_mul_f32_e32 v50, v50, v54
	v_add_f32_e32 v54, 1.0, v59
	v_mul_f32_e32 v58, 0xbfb8aa3b, v56
	v_rcp_f32_e32 v54, v54
	v_exp_f32_e32 v58, v58
	v_mul_f32_e32 v59, 0xbfb8aa3b, v57
	v_exp_f32_e32 v59, v59
	v_mul_f32_e32 v54, v55, v54
	v_add_f32_e32 v55, 1.0, v58
	v_rcp_f32_e32 v55, v55
	v_add_f32_e32 v58, 1.0, v59
	v_rcp_f32_e32 v58, v58
	v_mul_f32_e32 v51, v51, v54
	v_mul_f32_e32 v54, v56, v55
	v_mul_f32_e32 v52, v52, v54
	v_mul_f32_e32 v54, v57, v58
	v_cvt_pk_bf16_f32 v50, v50, v51
	v_add_u32_e32 v58, 0xa0, v201
	v_mul_f32_e32 v53, v53, v54
	v_cvt_pk_bf16_f32 v51, v52, v53
	global_store_dwordx2 v[60:61], v[50:51], off offset:32 nt
	v_lshlrev_b32_e32 v50, 1, v58
	v_ashrrev_i32_e32 v51, 31, v50
	v_lshl_add_u64 v[50:51], v[50:51], 2, s[82:83]
	v_mov_b32_e32 v50, v224
	v_mov_b32_e32 v51, v225
	v_pk_mul_f32 v[52:53], v[66:67], s[46:47] op_sel_hi:[1,0]
	s_nop 0
	v_mov_b32_e32 v55, v52
	v_mov_b32_e32 v57, v53
	v_pk_fma_f32 v[46:47], v[154:155], v[52:53], v[46:47] op_sel_hi:[1,0,1] neg_lo:[1,0,0] neg_hi:[1,0,0]
	v_pk_fma_f32 v[48:49], v[156:157], v[52:53], v[48:49] op_sel_hi:[1,0,1]
	v_pk_fma_f32 v[44:45], v[148:149], v[52:53], v[44:45] op_sel_hi:[1,0,1]
	v_pk_fma_f32 v[42:43], v[146:147], v[52:53], v[42:43] op_sel_hi:[1,0,1] neg_lo:[1,0,0] neg_hi:[1,0,0]
	v_pk_fma_f32 v[38:39], v[138:139], v[52:53], v[38:39] op_sel_hi:[1,0,1] neg_lo:[1,0,0] neg_hi:[1,0,0]
	v_pk_fma_f32 v[40:41], v[118:119], v[52:53], v[40:41] op_sel_hi:[1,0,1]
	v_pk_fma_f32 v[34:35], v[126:127], v[52:53], v[34:35] op_sel_hi:[1,0,1] neg_lo:[1,0,0] neg_hi:[1,0,0]
	v_pk_fma_f32 v[36:37], v[114:115], v[52:53], v[36:37] op_sel_hi:[1,0,1]
	v_pk_mul_f32 v[50:51], v[50:51], s[46:47] op_sel_hi:[1,0]
	s_nop 0
	v_mov_b32_e32 v54, v50
	v_mov_b32_e32 v56, v51
	v_pk_fma_f32 v[54:55], v[54:55], v[54:55], v[56:57] neg_lo:[1,0,0] neg_hi:[1,0,0]
	v_pk_fma_f32 v[30:31], v[154:155], v[50:51], v[30:31] op_sel_hi:[1,0,1] neg_lo:[1,0,0] neg_hi:[1,0,0]
	v_pk_add_f32 v[54:55], v[54:55], s[52:53] op_sel_hi:[1,0]
	v_pk_fma_f32 v[32:33], v[156:157], v[50:51], v[32:33] op_sel_hi:[1,0,1]
	v_mul_f32_e32 v56, 0x4b800000, v55
	v_cmp_gt_f32_e32 vcc, s63, v55
	v_pk_fma_f32 v[26:27], v[146:147], v[50:51], v[26:27] op_sel_hi:[1,0,1] neg_lo:[1,0,0] neg_hi:[1,0,0]
	v_pk_fma_f32 v[28:29], v[148:149], v[50:51], v[28:29] op_sel_hi:[1,0,1]
	v_cndmask_b32_e32 v55, v55, v56, vcc
	v_rsq_f32_e32 v55, v55
	v_pk_fma_f32 v[22:23], v[138:139], v[50:51], v[22:23] op_sel_hi:[1,0,1] neg_lo:[1,0,0] neg_hi:[1,0,0]
	v_pk_fma_f32 v[24:25], v[118:119], v[50:51], v[24:25] op_sel_hi:[1,0,1]
	v_pk_fma_f32 v[18:19], v[126:127], v[50:51], v[18:19] op_sel_hi:[1,0,1] neg_lo:[1,0,0] neg_hi:[1,0,0]
	v_mul_f32_e32 v56, 0x45800000, v55
	v_cndmask_b32_e32 v56, v55, v56, vcc
	v_pk_fma_f32 v[46:47], v[46:47], v[56:57], v[158:159] op_sel_hi:[1,0,1]
	v_pk_fma_f32 v[48:49], v[48:49], v[56:57], v[160:161] op_sel_hi:[1,0,1]
	v_mul_f32_e32 v55, 0xbfb8aa3b, v46
	v_exp_f32_e32 v55, v55
	v_pk_fma_f32 v[44:45], v[44:45], v[56:57], v[152:153] op_sel_hi:[1,0,1]
	v_mul_f32_e32 v57, 0xbfb8aa3b, v47
	v_exp_f32_e32 v57, v57
	v_add_f32_e32 v55, 1.0, v55
	v_rcp_f32_e32 v55, v55
	v_cmp_gt_f32_e32 vcc, s63, v54
	v_pk_fma_f32 v[42:43], v[42:43], v[56:57], v[150:151] op_sel_hi:[1,0,1]
	v_pk_fma_f32 v[20:21], v[114:115], v[50:51], v[20:21] op_sel_hi:[1,0,1]
	v_mul_f32_e32 v46, v46, v55
	v_mul_f32_e32 v42, v42, v46
	v_add_f32_e32 v46, 1.0, v57
	v_mul_f32_e32 v55, 0xbfb8aa3b, v48
	v_rcp_f32_e32 v46, v46
	v_exp_f32_e32 v55, v55
	v_mul_f32_e32 v57, 0xbfb8aa3b, v49
	v_exp_f32_e32 v57, v57
	v_mul_f32_e32 v46, v47, v46
	v_add_f32_e32 v47, 1.0, v55
	v_rcp_f32_e32 v47, v47
	v_add_f32_e32 v55, 1.0, v57
	v_rcp_f32_e32 v55, v55
	v_mul_f32_e32 v43, v43, v46
	v_mul_f32_e32 v46, v48, v47
	v_mul_f32_e32 v44, v44, v46
	v_mul_f32_e32 v46, v49, v55
	v_mul_f32_e32 v45, v45, v46
	v_cvt_pk_bf16_f32 v42, v42, v43
	v_cvt_pk_bf16_f32 v43, v44, v45
	v_mad_i64_i32 v[44:45], s[0:1], v68, s64, v[176:177]
	v_lshl_add_u64 v[44:45], v[44:45], 0, v[178:179]
	v_pk_fma_f32 v[38:39], v[38:39], v[56:57], v[142:143] op_sel_hi:[1,0,1]
	global_store_dwordx2 v[44:45], v[42:43], off nt
	v_mul_f32_e32 v42, 0xbfb8aa3b, v38
	v_exp_f32_e32 v42, v42
	v_mul_f32_e32 v43, 0xbfb8aa3b, v39
	v_exp_f32_e32 v43, v43
	v_pk_fma_f32 v[40:41], v[40:41], v[56:57], v[144:145] op_sel_hi:[1,0,1]
	v_add_f32_e32 v42, 1.0, v42
	v_rcp_f32_e32 v42, v42
	v_pk_fma_f32 v[34:35], v[34:35], v[56:57], v[122:123] op_sel_hi:[1,0,1]
	v_pk_fma_f32 v[36:37], v[36:37], v[56:57], v[124:125] op_sel_hi:[1,0,1]
	v_mul_f32_e32 v38, v38, v42
	v_mul_f32_e32 v34, v34, v38
	v_add_f32_e32 v38, 1.0, v43
	v_mul_f32_e32 v42, 0xbfb8aa3b, v40
	v_rcp_f32_e32 v38, v38
	v_exp_f32_e32 v42, v42
	v_mul_f32_e32 v43, 0xbfb8aa3b, v41
	v_exp_f32_e32 v43, v43
	v_mul_f32_e32 v38, v39, v38
	v_add_f32_e32 v39, 1.0, v42
	v_rcp_f32_e32 v39, v39
	v_add_f32_e32 v42, 1.0, v43
	v_rcp_f32_e32 v42, v42
	v_mul_f32_e32 v35, v35, v38
	v_mul_f32_e32 v38, v40, v39
	v_mul_f32_e32 v36, v36, v38
	v_mul_f32_e32 v38, v41, v42
	v_mul_f32_e32 v37, v37, v38
	v_cvt_pk_bf16_f32 v34, v34, v35
	v_cvt_pk_bf16_f32 v35, v36, v37
	v_add_u32_e32 v37, 0xb0, v201
	global_store_dwordx2 v[44:45], v[34:35], off offset:32 nt
	v_lshlrev_b32_e32 v34, 1, v37
	v_ashrrev_i32_e32 v35, 31, v34
	v_lshl_add_u64 v[34:35], v[34:35], 2, s[82:83]
	v_mov_b32_e32 v34, v226
	v_mov_b32_e32 v35, v227
	v_mul_f32_e32 v36, 0x4b800000, v54
	v_cndmask_b32_e32 v36, v54, v36, vcc
	v_rsq_f32_e32 v36, v36
	s_nop 0
	v_mul_f32_e32 v38, 0x45800000, v36
	v_cndmask_b32_e32 v36, v36, v38, vcc
	v_pk_fma_f32 v[30:31], v[30:31], v[36:37], v[158:159] op_sel_hi:[1,0,1]
	v_pk_fma_f32 v[32:33], v[32:33], v[36:37], v[160:161] op_sel_hi:[1,0,1]
	v_mul_f32_e32 v38, 0xbfb8aa3b, v30
	v_exp_f32_e32 v38, v38
	v_mul_f32_e32 v39, 0xbfb8aa3b, v31
	v_exp_f32_e32 v39, v39
	v_pk_fma_f32 v[26:27], v[26:27], v[36:37], v[150:151] op_sel_hi:[1,0,1]
	v_add_f32_e32 v38, 1.0, v38
	v_rcp_f32_e32 v38, v38
	v_pk_fma_f32 v[28:29], v[28:29], v[36:37], v[152:153] op_sel_hi:[1,0,1]
	v_pk_fma_f32 v[22:23], v[22:23], v[36:37], v[142:143] op_sel_hi:[1,0,1]
	v_pk_fma_f32 v[24:25], v[24:25], v[36:37], v[144:145] op_sel_hi:[1,0,1]
	v_mul_f32_e32 v30, v30, v38
	v_mul_f32_e32 v26, v26, v30
	v_add_f32_e32 v30, 1.0, v39
	v_mul_f32_e32 v38, 0xbfb8aa3b, v32
	v_rcp_f32_e32 v30, v30
	v_exp_f32_e32 v38, v38
	v_mul_f32_e32 v39, 0xbfb8aa3b, v33
	v_exp_f32_e32 v39, v39
	v_mul_f32_e32 v30, v31, v30
	v_add_f32_e32 v31, 1.0, v38
	v_rcp_f32_e32 v31, v31
	v_add_f32_e32 v38, 1.0, v39
	v_rcp_f32_e32 v38, v38
	v_mul_f32_e32 v27, v27, v30
	v_mul_f32_e32 v30, v32, v31
	v_mul_f32_e32 v28, v28, v30
	v_mul_f32_e32 v30, v33, v38
	v_mul_f32_e32 v29, v29, v30
	v_mul_f32_e32 v30, 0xbfb8aa3b, v22
	v_exp_f32_e32 v30, v30
	v_mul_f32_e32 v31, 0xbfb8aa3b, v23
	v_exp_f32_e32 v31, v31
	v_pk_fma_f32 v[18:19], v[18:19], v[36:37], v[122:123] op_sel_hi:[1,0,1]
	v_add_f32_e32 v30, 1.0, v30
	v_rcp_f32_e32 v30, v30
	v_pk_fma_f32 v[20:21], v[20:21], v[36:37], v[124:125] op_sel_hi:[1,0,1]
	v_cvt_pk_bf16_f32 v26, v26, v27
	v_cvt_pk_bf16_f32 v27, v28, v29
	v_mul_f32_e32 v22, v22, v30
	v_mul_f32_e32 v18, v18, v22
	v_add_f32_e32 v22, 1.0, v31
	v_mul_f32_e32 v30, 0xbfb8aa3b, v24
	v_rcp_f32_e32 v22, v22
	v_exp_f32_e32 v30, v30
	v_mul_f32_e32 v31, 0xbfb8aa3b, v25
	v_exp_f32_e32 v31, v31
	v_mul_f32_e32 v22, v23, v22
	v_add_f32_e32 v23, 1.0, v30
	v_rcp_f32_e32 v23, v23
	v_add_f32_e32 v30, 1.0, v31
	v_rcp_f32_e32 v30, v30
	v_mul_f32_e32 v19, v19, v22
	v_mul_f32_e32 v22, v24, v23
	v_mul_f32_e32 v22, v20, v22
	v_mul_f32_e32 v20, v25, v30
	v_mul_f32_e32 v23, v21, v20
	v_cvt_pk_bf16_f32 v18, v18, v19
	v_mad_i64_i32 v[28:29], s[0:1], v58, s64, v[176:177]
	v_lshl_add_u64 v[28:29], v[28:29], 0, v[178:179]
	v_pk_mul_f32 v[20:21], v[34:35], s[46:47] op_sel_hi:[1,0]
	s_nop 0
	v_fma_f32 v19, -v20, v20, v21
	v_add_f32_e32 v19, 0x3727c5ac, v19
	v_mul_f32_e32 v24, 0x4b800000, v19
	v_cmp_gt_f32_e32 vcc, s63, v19
	v_pk_fma_f32 v[14:15], v[154:155], v[20:21], v[14:15] op_sel_hi:[1,0,1] neg_lo:[1,0,0] neg_hi:[1,0,0]
	v_pk_fma_f32 v[16:17], v[156:157], v[20:21], v[16:17] op_sel_hi:[1,0,1]
	v_cndmask_b32_e32 v19, v19, v24, vcc
	v_rsq_f32_e32 v24, v19
	v_cvt_pk_bf16_f32 v19, v22, v23
	global_store_dwordx2 v[28:29], v[26:27], off nt
	global_store_dwordx2 v[28:29], v[18:19], off offset:32 nt
	v_pk_fma_f32 v[12:13], v[148:149], v[20:21], v[12:13] op_sel_hi:[1,0,1]
	v_mul_f32_e32 v18, 0x45800000, v24
	v_cndmask_b32_e32 v18, v24, v18, vcc
	v_pk_fma_f32 v[14:15], v[14:15], v[18:19], v[158:159] op_sel_hi:[1,0,1]
	v_pk_fma_f32 v[16:17], v[16:17], v[18:19], v[160:161] op_sel_hi:[1,0,1]
	v_mul_f32_e32 v19, 0xbfb8aa3b, v14
	v_exp_f32_e32 v19, v19
	v_mul_f32_e32 v22, 0xbfb8aa3b, v15
	v_exp_f32_e32 v22, v22
	v_pk_fma_f32 v[10:11], v[146:147], v[20:21], v[10:11] op_sel_hi:[1,0,1] neg_lo:[1,0,0] neg_hi:[1,0,0]
	v_pk_fma_f32 v[12:13], v[12:13], v[18:19], v[152:153] op_sel_hi:[1,0,1]
	v_add_f32_e32 v19, 1.0, v19
	v_rcp_f32_e32 v19, v19
	v_pk_fma_f32 v[6:7], v[138:139], v[20:21], v[6:7] op_sel_hi:[1,0,1] neg_lo:[1,0,0] neg_hi:[1,0,0]
	v_pk_fma_f32 v[8:9], v[118:119], v[20:21], v[8:9] op_sel_hi:[1,0,1]
	v_pk_fma_f32 v[2:3], v[126:127], v[20:21], v[2:3] op_sel_hi:[1,0,1] neg_lo:[1,0,0] neg_hi:[1,0,0]
	v_pk_fma_f32 v[10:11], v[10:11], v[18:19], v[150:151] op_sel_hi:[1,0,1]
	v_mul_f32_e32 v14, v14, v19
	v_mul_f32_e32 v10, v10, v14
	v_add_f32_e32 v14, 1.0, v22
	v_mul_f32_e32 v19, 0xbfb8aa3b, v16
	v_rcp_f32_e32 v14, v14
	v_exp_f32_e32 v19, v19
	v_mul_f32_e32 v22, 0xbfb8aa3b, v17
	v_exp_f32_e32 v22, v22
	v_mul_f32_e32 v14, v15, v14
	v_add_f32_e32 v15, 1.0, v19
	v_rcp_f32_e32 v15, v15
	v_add_f32_e32 v19, 1.0, v22
	v_rcp_f32_e32 v19, v19
	v_mul_f32_e32 v11, v11, v14
	v_mul_f32_e32 v14, v16, v15
	v_mul_f32_e32 v12, v12, v14
	v_mul_f32_e32 v14, v17, v19
	v_mul_f32_e32 v13, v13, v14
	v_cvt_pk_bf16_f32 v10, v10, v11
	v_cvt_pk_bf16_f32 v11, v12, v13
	v_mad_i64_i32 v[12:13], s[0:1], v37, s64, v[176:177]
	v_lshl_add_u64 v[12:13], v[12:13], 0, v[178:179]
	v_pk_fma_f32 v[6:7], v[6:7], v[18:19], v[142:143] op_sel_hi:[1,0,1]
	global_store_dwordx2 v[12:13], v[10:11], off nt
	v_mul_f32_e32 v10, 0xbfb8aa3b, v6
	v_exp_f32_e32 v10, v10
	v_mul_f32_e32 v11, 0xbfb8aa3b, v7
	v_exp_f32_e32 v11, v11
	v_pk_fma_f32 v[8:9], v[8:9], v[18:19], v[144:145] op_sel_hi:[1,0,1]
	v_add_f32_e32 v10, 1.0, v10
	v_rcp_f32_e32 v10, v10
	v_pk_fma_f32 v[2:3], v[2:3], v[18:19], v[122:123] op_sel_hi:[1,0,1]
	v_pk_fma_f32 v[4:5], v[114:115], v[20:21], v[4:5] op_sel_hi:[1,0,1]
	s_and_b64 vcc, exec, s[6:7]
	v_mul_f32_e32 v6, v6, v10
	v_mul_f32_e32 v2, v2, v6
	v_add_f32_e32 v6, 1.0, v11
	v_mul_f32_e32 v10, 0xbfb8aa3b, v8
	v_rcp_f32_e32 v6, v6
	v_exp_f32_e32 v10, v10
	v_mul_f32_e32 v11, 0xbfb8aa3b, v9
	v_exp_f32_e32 v11, v11
	v_mul_f32_e32 v6, v7, v6
	v_add_f32_e32 v7, 1.0, v10
	v_rcp_f32_e32 v7, v7
	v_add_f32_e32 v10, 1.0, v11
	v_rcp_f32_e32 v10, v10
	v_pk_fma_f32 v[4:5], v[4:5], v[18:19], v[124:125] op_sel_hi:[1,0,1]
	v_mul_f32_e32 v3, v3, v6
	v_mul_f32_e32 v6, v8, v7
	v_mul_f32_e32 v4, v4, v6
	v_mul_f32_e32 v6, v9, v10
	v_mul_f32_e32 v5, v5, v6
	v_cvt_pk_bf16_f32 v2, v2, v3
	v_cvt_pk_bf16_f32 v3, v4, v5
	global_store_dwordx2 v[12:13], v[2:3], off offset:32 nt
	s_cbranch_vccnz .LBB0_1105
